# speedup vs baseline: 1.0060x; 1.0056x over previous
; #define SCHED() __builtin_amdgcn_sched_barrier(0)
; __device__ __forceinline__ void gqa_items(const Params& p, int l, int L, char* shm, const int tid, const int local, const int G, const int nGQ) {
;     ...
;     if (it == local) asm volatile("s_waitcnt vmcnt(2)" ::: "memory"); else asm volatile("s_waitcnt vmcnt(4)" ::: "memory");
;     __builtin_amdgcn_s_barrier(); asm volatile("" ::: "memory"); SCHED();
.LBB0_532:
	s_andn2_b64 vcc, exec, s[0:1]
	s_cbranch_vccnz .LBB0_534
	s_waitcnt vmcnt(0)

; #define SCHED() __builtin_amdgcn_sched_barrier(0)
; #define GLOADS(KS, VS, t, slot) do { char* lb_ = shm + (slot) * 16384 + wid * 1024;                                  \
;     __builtin_amdgcn_global_load_lds((const unsigned*)((KS) + (size_t)(t) * 64 * PW), (unsigned*)(lb_), 16, 0, 0);    \
;     __builtin_amdgcn_global_load_lds((const unsigned*)((VS) + (t) * 64), (unsigned*)(lb_ + 8192), 16, 0, 0); } while (0)
; #define PART(P0, P1) do { _Pragma("unroll") for (int r = 0; r < 16; ++r) FMK(P0[r]);                             \
;     _Pragma("unroll") for (int r = 0; r < 16; ++r) FMK(P1[r]);                                                    \
;     _Pragma("unroll") for (int r = 0; r < 16; ++r) P0[r] = __builtin_amdgcn_exp2f(P0[r]); } while (0)
; #define EXP1(P1) do { _Pragma("unroll") for (int r = 0; r < 16; ++r) P1[r] = __builtin_amdgcn_exp2f(P1[r]); } while (0)
; #define PACK(P0, P1) do { float ps_ = 0.f; _Pragma("unroll") for (int r = 0; r < 16; ++r) ps_ += P0[r] + P1[r]; lsum += ps_;  \
;     PK4(P0, 0, pa0); PK4(P0, 8, pa1); PK4(P1, 0, pa2); PK4(P1, 8, pa3); } while (0)
; #define KFR(slot) do { const char* Kc = shm + (slot) * 16384;                                                      \
;     _Pragma("unroll") for (int d0 = 0; d0 < 4; ++d0) { fr_[d0 * 2] = *(const bf16x8*)(Kc + roff[d0]); fr_[d0 * 2 + 1] = *(const bf16x8*)(Kc + roff[d0] + 4096); } } while (0)
; #define VFR(slot) do { const char* Vc = shm + (slot) * 16384 + 8192;                                               \
;     _Pragma("unroll") for (int ks = 0; ks < 4; ++ks) { fr_[ks * 2] = *(const bf16x8*)(Vc + roff[ks]); fr_[ks * 2 + 1] = *(const bf16x8*)(Vc + roff[ks] + 4096); } } while (0)
; __device__ __forceinline__ void gqa_items(const Params& p, int l, int L, char* shm, const int tid, const int local, const int G, const int nGQ) {
;     ...
;     for (int j = 0; j < NT; ++j) {
;       if (j + 2 < NT) { const int ns_ = (cur == 0) ? 2 : cur - 1; GLOADS(Ks, Vs, j + 2, ns_); }
;       SCHED(); KFR(cur); SCHED();
;       QKT(pA0, pA1); SCHED();
;       PART(pA0, pA1); EXP1(pA1); SCHED();
;       VFR(cur); SCHED();
;       PACK(pA0, pA1); SCHED();
.LBB0_536:
	s_lshl_b32 s16, s14, 14
	v_add_u32_e32 v224, s16, v109
	v_add_u32_e32 v225, s16, v120
	v_add_u32_e32 v226, s16, v121
	v_add_u32_e32 v227, s16, v122
	ds_read_b128 v[192:195], v224
	ds_read_b128 v[196:199], v224 offset:4096
	ds_read_b128 v[200:203], v225
	ds_read_b128 v[204:207], v225 offset:4096
	ds_read_b128 v[208:211], v226
	ds_read_b128 v[212:215], v226 offset:4096
	ds_read_b128 v[216:219], v227
	ds_read_b128 v[220:223], v227 offset:4096
	s_add_i32 s2, s15, 2
	s_cmp_ge_u32 s2, s96
	s_cbranch_scc1 .Lgq_nold
	s_add_i32 s2, s14, 2
	s_and_b32 s2, s2, 3
	s_lshl_b32 s2, s2, 14
	s_add_i32 s2, s7, s2
	s_mov_b32 m0, s2
	v_lshl_add_u64 v[228:229], s[58:59], 1, v[74:75]
	global_load_lds_dwordx4 v[78:79], off
	s_add_i32 m0, s2, 0x2000
	s_nop 0
	global_load_lds_dwordx4 v[228:229], off
	v_lshl_add_u64 v[78:79], v[78:79], 0, s[92:93]
	s_add_i32 s58, s58, 64
	s_add_i32 s2, s14, 3
	s_and_b32 s2, s2, 3
	s_lshl_b32 s2, s2, 14
	s_add_i32 s2, s7, s2
	s_mov_b32 m0, s2
	v_lshl_add_u64 v[228:229], s[58:59], 1, v[74:75]
	global_load_lds_dwordx4 v[78:79], off
	s_add_i32 m0, s2, 0x2000
	s_nop 0
	global_load_lds_dwordx4 v[228:229], off
	v_lshl_add_u64 v[78:79], v[78:79], 0, s[92:93]
	s_add_i32 s58, s58, 64
.Lgq_nold:
	s_waitcnt lgkmcnt(7)
	v_mfma_f32_32x32x16_bf16 v[34:49], v[192:195], v[50:53], 0
	ds_read_b128 v[144:147], v224 offset:8192
	s_waitcnt lgkmcnt(7)
	v_mfma_f32_32x32x16_bf16 v[128:143], v[196:199], v[50:53], 0
	ds_read_b128 v[148:151], v224 offset:12288
	s_waitcnt lgkmcnt(7)
	v_mfma_f32_32x32x16_bf16 v[34:49], v[200:203], v[54:57], v[34:49]
	ds_read_b128 v[152:155], v225 offset:8192
	s_waitcnt lgkmcnt(7)
	v_mfma_f32_32x32x16_bf16 v[128:143], v[204:207], v[54:57], v[128:143]
	ds_read_b128 v[156:159], v225 offset:12288
	s_waitcnt lgkmcnt(7)
	v_mfma_f32_32x32x16_bf16 v[34:49], v[208:211], v[58:61], v[34:49]
	ds_read_b128 v[160:163], v226 offset:8192
	s_waitcnt lgkmcnt(7)
	v_mfma_f32_32x32x16_bf16 v[128:143], v[212:215], v[58:61], v[128:143]
	ds_read_b128 v[164:167], v226 offset:12288
	s_waitcnt lgkmcnt(7)
	v_mfma_f32_32x32x16_bf16 v[34:49], v[216:219], v[62:65], v[34:49]
	ds_read_b128 v[168:171], v227 offset:8192
	s_waitcnt lgkmcnt(7)
	v_mfma_f32_32x32x16_bf16 v[128:143], v[220:223], v[62:65], v[128:143]
	ds_read_b128 v[172:175], v227 offset:12288
	s_add_i32 s3, s14, 1
	s_and_b32 s3, s3, 3
	s_lshl_b32 s3, s3, 14
	v_add_u32_e32 v230, s3, v109
	v_add_u32_e32 v231, s3, v120
	v_add_u32_e32 v232, s3, v121
	v_add_u32_e32 v233, s3, v122
	s_waitcnt lgkmcnt(4)
	ds_read_b128 v[192:195], v230
	ds_read_b128 v[196:199], v230 offset:4096
	ds_read_b128 v[200:203], v231
	ds_read_b128 v[204:207], v231 offset:4096
	ds_read_b128 v[208:211], v232
	ds_read_b128 v[212:215], v232 offset:4096
	ds_read_b128 v[216:219], v233
	ds_read_b128 v[220:223], v233 offset:4096
	v_fmamk_f32 v34, v34, 0x3e38aa3b, v71
	v_fmamk_f32 v35, v35, 0x3e38aa3b, v71
	v_fmamk_f32 v36, v36, 0x3e38aa3b, v71
	v_fmamk_f32 v37, v37, 0x3e38aa3b, v71
	v_fmamk_f32 v38, v38, 0x3e38aa3b, v71
	v_fmamk_f32 v39, v39, 0x3e38aa3b, v71
	v_fmamk_f32 v40, v40, 0x3e38aa3b, v71
	v_fmamk_f32 v41, v41, 0x3e38aa3b, v71
	v_fmamk_f32 v42, v42, 0x3e38aa3b, v71
	v_fmamk_f32 v43, v43, 0x3e38aa3b, v71
	v_fmamk_f32 v44, v44, 0x3e38aa3b, v71
	v_fmamk_f32 v45, v45, 0x3e38aa3b, v71
	v_fmamk_f32 v46, v46, 0x3e38aa3b, v71
	v_fmamk_f32 v47, v47, 0x3e38aa3b, v71
	v_fmamk_f32 v48, v48, 0x3e38aa3b, v71
	v_fmamk_f32 v49, v49, 0x3e38aa3b, v71
	v_exp_f32_e32 v34, v34
	v_exp_f32_e32 v35, v35
	v_exp_f32_e32 v36, v36
	v_exp_f32_e32 v37, v37
	v_exp_f32_e32 v38, v38
	v_exp_f32_e32 v39, v39
	v_exp_f32_e32 v40, v40
	v_exp_f32_e32 v41, v41
	v_exp_f32_e32 v42, v42
	v_exp_f32_e32 v43, v43
	v_exp_f32_e32 v44, v44
	v_exp_f32_e32 v45, v45
	v_exp_f32_e32 v46, v46
	v_exp_f32_e32 v47, v47
	v_exp_f32_e32 v48, v48
	v_exp_f32_e32 v49, v49
	v_cvt_pk_bf16_f32 v176, v34, v35
	v_cvt_pk_bf16_f32 v177, v36, v37
	v_cvt_pk_bf16_f32 v178, v38, v39
	v_cvt_pk_bf16_f32 v179, v40, v41
	v_cvt_pk_bf16_f32 v180, v42, v43
	v_cvt_pk_bf16_f32 v181, v44, v45
	v_cvt_pk_bf16_f32 v182, v46, v47
	v_cvt_pk_bf16_f32 v183, v48, v49
	v_permlane32_swap_b32_e32 v176, v178
	v_permlane32_swap_b32_e32 v177, v179
	v_permlane32_swap_b32_e32 v180, v182
	v_permlane32_swap_b32_e32 v181, v183
	s_waitcnt lgkmcnt(8)
; #define SCHED() __builtin_amdgcn_sched_barrier(0)
; #define GLOADS(KS, VS, t, slot) do { char* lb_ = shm + (slot) * 16384 + wid * 1024;                                  \
;     __builtin_amdgcn_global_load_lds((const unsigned*)((KS) + (size_t)(t) * 64 * PW), (unsigned*)(lb_), 16, 0, 0);    \
;     __builtin_amdgcn_global_load_lds((const unsigned*)((VS) + (t) * 64), (unsigned*)(lb_ + 8192), 16, 0, 0); } while (0)
; #define PART(P0, P1) do { _Pragma("unroll") for (int r = 0; r < 16; ++r) FMK(P0[r]);                             \
;     _Pragma("unroll") for (int r = 0; r < 16; ++r) FMK(P1[r]);                                                    \
;     _Pragma("unroll") for (int r = 0; r < 16; ++r) P0[r] = __builtin_amdgcn_exp2f(P0[r]); } while (0)
; #define EXP1(P1) do { _Pragma("unroll") for (int r = 0; r < 16; ++r) P1[r] = __builtin_amdgcn_exp2f(P1[r]); } while (0)
; #define PACK(P0, P1) do { float ps_ = 0.f; _Pragma("unroll") for (int r = 0; r < 16; ++r) ps_ += P0[r] + P1[r]; lsum += ps_;  \
;     PK4(P0, 0, pa0); PK4(P0, 8, pa1); PK4(P1, 0, pa2); PK4(P1, 8, pa3); } while (0)
; #define KFR(slot) do { const char* Kc = shm + (slot) * 16384;                                                      \
;     _Pragma("unroll") for (int d0 = 0; d0 < 4; ++d0) { fr_[d0 * 2] = *(const bf16x8*)(Kc + roff[d0]); fr_[d0 * 2 + 1] = *(const bf16x8*)(Kc + roff[d0] + 4096); } } while (0)
; #define VFR(slot) do { const char* Vc = shm + (slot) * 16384 + 8192;                                               \
;     _Pragma("unroll") for (int ks = 0; ks < 4; ++ks) { fr_[ks * 2] = *(const bf16x8*)(Vc + roff[ks]); fr_[ks * 2 + 1] = *(const bf16x8*)(Vc + roff[ks] + 4096); } } while (0)
; #define PVM() do { PV1(pa0, 0); PV1(pa1, 1); PV1(pa2, 2); PV1(pa3, 3); } while (0)
; __device__ __forceinline__ void gqa_items(const Params& p, int l, int L, char* shm, const int tid, const int local, const int G, const int nGQ) {
;     ...
;     for (int j = 0; j < NT; ++j) {
;       if (j + 2 < NT) { const int ns_ = (cur == 0) ? 2 : cur - 1; GLOADS(Ks, Vs, j + 2, ns_); }
;       SCHED(); KFR(cur); SCHED();
;       QKT(pA0, pA1); SCHED();
;       PART(pA0, pA1); EXP1(pA1); SCHED();
;       VFR(cur); SCHED();
;       PACK(pA0, pA1); SCHED();
;       PVM();
	v_mfma_f32_32x32x16_bf16 v[18:33], v[176:179], v[144:147], v[18:33]
	v_fmamk_f32 v128, v128, 0x3e38aa3b, v71
	v_fmamk_f32 v129, v129, 0x3e38aa3b, v71
	v_fmamk_f32 v130, v130, 0x3e38aa3b, v71
	v_fmamk_f32 v131, v131, 0x3e38aa3b, v71
	v_fmamk_f32 v132, v132, 0x3e38aa3b, v71
	v_fmamk_f32 v133, v133, 0x3e38aa3b, v71
	v_fmamk_f32 v134, v134, 0x3e38aa3b, v71
	v_fmamk_f32 v135, v135, 0x3e38aa3b, v71
	v_mfma_f32_32x32x16_bf16 v[2:17], v[176:179], v[148:151], v[2:17]
	v_fmamk_f32 v136, v136, 0x3e38aa3b, v71
	v_fmamk_f32 v137, v137, 0x3e38aa3b, v71
	v_fmamk_f32 v138, v138, 0x3e38aa3b, v71
	v_fmamk_f32 v139, v139, 0x3e38aa3b, v71
	v_fmamk_f32 v140, v140, 0x3e38aa3b, v71
	v_fmamk_f32 v141, v141, 0x3e38aa3b, v71
	v_fmamk_f32 v142, v142, 0x3e38aa3b, v71
	v_fmamk_f32 v143, v143, 0x3e38aa3b, v71
	v_mfma_f32_32x32x16_bf16 v[18:33], v[180:183], v[152:155], v[18:33]
	v_exp_f32_e32 v128, v128
	v_exp_f32_e32 v129, v129
	v_exp_f32_e32 v130, v130
	v_exp_f32_e32 v131, v131
	v_exp_f32_e32 v132, v132
	v_exp_f32_e32 v133, v133
	v_exp_f32_e32 v134, v134
	v_exp_f32_e32 v135, v135
	v_mfma_f32_32x32x16_bf16 v[2:17], v[180:183], v[156:159], v[2:17]
	v_exp_f32_e32 v136, v136
	v_exp_f32_e32 v137, v137
	v_exp_f32_e32 v138, v138
	v_exp_f32_e32 v139, v139
	v_exp_f32_e32 v140, v140
	v_exp_f32_e32 v141, v141
	v_exp_f32_e32 v142, v142
	v_exp_f32_e32 v143, v143
	v_cvt_pk_bf16_f32 v184, v128, v129
	v_cvt_pk_bf16_f32 v185, v130, v131
	v_cvt_pk_bf16_f32 v186, v132, v133
	v_cvt_pk_bf16_f32 v187, v134, v135
	v_cvt_pk_bf16_f32 v188, v136, v137
	v_cvt_pk_bf16_f32 v189, v138, v139
	v_cvt_pk_bf16_f32 v190, v140, v141
	v_cvt_pk_bf16_f32 v191, v142, v143
	v_permlane32_swap_b32_e32 v184, v186
	v_permlane32_swap_b32_e32 v185, v187
	v_permlane32_swap_b32_e32 v188, v190
	v_permlane32_swap_b32_e32 v189, v191
	v_add_f32_e32 v34, v34, v128
	v_add_f32_e32 v35, v35, v129
	v_mfma_f32_32x32x16_bf16 v[18:33], v[184:187], v[160:163], v[18:33]
	v_add_f32_e32 v36, v36, v130
	v_add_f32_e32 v37, v37, v131
	v_add_f32_e32 v38, v38, v132
	v_add_f32_e32 v39, v39, v133
	v_add_f32_e32 v40, v40, v134
	v_add_f32_e32 v41, v41, v135
	v_add_f32_e32 v42, v42, v136
	v_add_f32_e32 v43, v43, v137
	v_mfma_f32_32x32x16_bf16 v[2:17], v[184:187], v[164:167], v[2:17]
	v_add_f32_e32 v44, v44, v138
	v_add_f32_e32 v45, v45, v139
	v_add_f32_e32 v46, v46, v140
	v_add_f32_e32 v47, v47, v141
	v_add_f32_e32 v48, v48, v142
	v_add_f32_e32 v49, v49, v143
	v_add_f32_e32 v35, v35, v34
	v_add_f32_e32 v36, v36, v35
	v_mfma_f32_32x32x16_bf16 v[18:33], v[188:191], v[168:171], v[18:33]
	v_add_f32_e32 v37, v37, v36
	v_add_f32_e32 v38, v38, v37
	v_add_f32_e32 v39, v39, v38
	v_add_f32_e32 v40, v40, v39
	v_add_f32_e32 v41, v41, v40
	v_add_f32_e32 v42, v42, v41
	v_add_f32_e32 v43, v43, v42
	v_add_f32_e32 v44, v44, v43
	v_mfma_f32_32x32x16_bf16 v[2:17], v[188:191], v[172:175], v[2:17]
	v_add_f32_e32 v45, v45, v44
	v_add_f32_e32 v46, v46, v45
	v_add_f32_e32 v47, v47, v46
	v_add_f32_e32 v48, v48, v47
	v_add_f32_e32 v49, v49, v48
	v_add_f32_e32 v127, v127, v49
	s_waitcnt lgkmcnt(0)
	v_mfma_f32_32x32x16_bf16 v[34:49], v[192:195], v[50:53], 0
	ds_read_b128 v[144:147], v230 offset:8192
	v_mfma_f32_32x32x16_bf16 v[128:143], v[196:199], v[50:53], 0
	ds_read_b128 v[148:151], v230 offset:12288
	v_mfma_f32_32x32x16_bf16 v[34:49], v[200:203], v[54:57], v[34:49]
	ds_read_b128 v[152:155], v231 offset:8192
	v_mfma_f32_32x32x16_bf16 v[128:143], v[204:207], v[54:57], v[128:143]
	ds_read_b128 v[156:159], v231 offset:12288
	v_mfma_f32_32x32x16_bf16 v[34:49], v[208:211], v[58:61], v[34:49]
	ds_read_b128 v[160:163], v232 offset:8192
	v_mfma_f32_32x32x16_bf16 v[128:143], v[212:215], v[58:61], v[128:143]
	ds_read_b128 v[164:167], v232 offset:12288
	v_mfma_f32_32x32x16_bf16 v[34:49], v[216:219], v[62:65], v[34:49]
	ds_read_b128 v[168:171], v233 offset:8192
	v_mfma_f32_32x32x16_bf16 v[128:143], v[220:223], v[62:65], v[128:143]
	ds_read_b128 v[172:175], v233 offset:12288
	s_nop 9
	v_fmamk_f32 v34, v34, 0x3e38aa3b, v71
	v_fmamk_f32 v35, v35, 0x3e38aa3b, v71
	v_fmamk_f32 v36, v36, 0x3e38aa3b, v71
	v_fmamk_f32 v37, v37, 0x3e38aa3b, v71
	v_fmamk_f32 v38, v38, 0x3e38aa3b, v71
	v_fmamk_f32 v39, v39, 0x3e38aa3b, v71
	v_fmamk_f32 v40, v40, 0x3e38aa3b, v71
	v_fmamk_f32 v41, v41, 0x3e38aa3b, v71
	v_fmamk_f32 v42, v42, 0x3e38aa3b, v71
	v_fmamk_f32 v43, v43, 0x3e38aa3b, v71
	v_fmamk_f32 v44, v44, 0x3e38aa3b, v71
	v_fmamk_f32 v45, v45, 0x3e38aa3b, v71
	v_fmamk_f32 v46, v46, 0x3e38aa3b, v71
	v_fmamk_f32 v47, v47, 0x3e38aa3b, v71
	v_fmamk_f32 v48, v48, 0x3e38aa3b, v71
	v_fmamk_f32 v49, v49, 0x3e38aa3b, v71
	v_exp_f32_e32 v34, v34
	v_exp_f32_e32 v35, v35
	v_exp_f32_e32 v36, v36
	v_exp_f32_e32 v37, v37
	v_exp_f32_e32 v38, v38
	v_exp_f32_e32 v39, v39
	v_exp_f32_e32 v40, v40
	v_exp_f32_e32 v41, v41
	v_exp_f32_e32 v42, v42
	v_exp_f32_e32 v43, v43
	v_exp_f32_e32 v44, v44
	v_exp_f32_e32 v45, v45
	v_exp_f32_e32 v46, v46
	v_exp_f32_e32 v47, v47
	v_exp_f32_e32 v48, v48
	v_exp_f32_e32 v49, v49
	v_cvt_pk_bf16_f32 v176, v34, v35
	v_cvt_pk_bf16_f32 v177, v36, v37
	v_cvt_pk_bf16_f32 v178, v38, v39
	v_cvt_pk_bf16_f32 v179, v40, v41
	v_cvt_pk_bf16_f32 v180, v42, v43
	v_cvt_pk_bf16_f32 v181, v44, v45
	v_cvt_pk_bf16_f32 v182, v46, v47
	v_cvt_pk_bf16_f32 v183, v48, v49
	v_permlane32_swap_b32_e32 v176, v178
	v_permlane32_swap_b32_e32 v177, v179
	v_permlane32_swap_b32_e32 v180, v182
	v_permlane32_swap_b32_e32 v181, v183
	s_waitcnt lgkmcnt(0)
; #define SCHED() __builtin_amdgcn_sched_barrier(0)
; #define GLOADS(KS, VS, t, slot) do { char* lb_ = shm + (slot) * 16384 + wid * 1024;                                  \
;     __builtin_amdgcn_global_load_lds((const unsigned*)((KS) + (size_t)(t) * 64 * PW), (unsigned*)(lb_), 16, 0, 0);    \
;     __builtin_amdgcn_global_load_lds((const unsigned*)((VS) + (t) * 64), (unsigned*)(lb_ + 8192), 16, 0, 0); } while (0)
; #define PART(P0, P1) do { _Pragma("unroll") for (int r = 0; r < 16; ++r) FMK(P0[r]);                             \
;     _Pragma("unroll") for (int r = 0; r < 16; ++r) FMK(P1[r]);                                                    \
;     _Pragma("unroll") for (int r = 0; r < 16; ++r) P0[r] = __builtin_amdgcn_exp2f(P0[r]); } while (0)
; #define EXP1(P1) do { _Pragma("unroll") for (int r = 0; r < 16; ++r) P1[r] = __builtin_amdgcn_exp2f(P1[r]); } while (0)
; #define PACK(P0, P1) do { float ps_ = 0.f; _Pragma("unroll") for (int r = 0; r < 16; ++r) ps_ += P0[r] + P1[r]; lsum += ps_;  \
;     PK4(P0, 0, pa0); PK4(P0, 8, pa1); PK4(P1, 0, pa2); PK4(P1, 8, pa3); } while (0)
; #define KFR(slot) do { const char* Kc = shm + (slot) * 16384;                                                      \
;     _Pragma("unroll") for (int d0 = 0; d0 < 4; ++d0) { fr_[d0 * 2] = *(const bf16x8*)(Kc + roff[d0]); fr_[d0 * 2 + 1] = *(const bf16x8*)(Kc + roff[d0] + 4096); } } while (0)
; #define PVM() do { PV1(pa0, 0); PV1(pa1, 1); PV1(pa2, 2); PV1(pa3, 3); } while (0)
; __device__ __forceinline__ void gqa_items(const Params& p, int l, int L, char* shm, const int tid, const int local, const int G, const int nGQ) {
;     ...
;     for (int j = 0; j < NT; ++j) {
;       if (j + 2 < NT) { const int ns_ = (cur == 0) ? 2 : cur - 1; GLOADS(Ks, Vs, j + 2, ns_); }
;       SCHED(); KFR(cur); SCHED();
;       QKT(pA0, pA1); SCHED();
;       PART(pA0, pA1); EXP1(pA1); SCHED();
;       VFR(cur); SCHED();
;       PACK(pA0, pA1); SCHED();
;       PVM();
;       SCHED();
;       if (j + 2 < NT) asm volatile("s_waitcnt vmcnt(2) lgkmcnt(0)" ::: "memory"); else asm volatile("s_waitcnt vmcnt(0) lgkmcnt(0)" ::: "memory");
;       __builtin_amdgcn_s_barrier(); asm volatile("" ::: "memory"); SCHED();
;       cur = (cur == 2) ? 0 : cur + 1;
;     }
	v_mfma_f32_32x32x16_bf16 v[18:33], v[176:179], v[144:147], v[18:33]
	v_fmamk_f32 v128, v128, 0x3e38aa3b, v71
	v_fmamk_f32 v129, v129, 0x3e38aa3b, v71
	v_fmamk_f32 v130, v130, 0x3e38aa3b, v71
	v_fmamk_f32 v131, v131, 0x3e38aa3b, v71
	v_fmamk_f32 v132, v132, 0x3e38aa3b, v71
	v_fmamk_f32 v133, v133, 0x3e38aa3b, v71
	v_fmamk_f32 v134, v134, 0x3e38aa3b, v71
	v_fmamk_f32 v135, v135, 0x3e38aa3b, v71
	v_mfma_f32_32x32x16_bf16 v[2:17], v[176:179], v[148:151], v[2:17]
	v_fmamk_f32 v136, v136, 0x3e38aa3b, v71
	v_fmamk_f32 v137, v137, 0x3e38aa3b, v71
	v_fmamk_f32 v138, v138, 0x3e38aa3b, v71
	v_fmamk_f32 v139, v139, 0x3e38aa3b, v71
	v_fmamk_f32 v140, v140, 0x3e38aa3b, v71
	v_fmamk_f32 v141, v141, 0x3e38aa3b, v71
	v_fmamk_f32 v142, v142, 0x3e38aa3b, v71
	v_fmamk_f32 v143, v143, 0x3e38aa3b, v71
	v_mfma_f32_32x32x16_bf16 v[18:33], v[180:183], v[152:155], v[18:33]
	v_exp_f32_e32 v128, v128
	v_exp_f32_e32 v129, v129
	v_exp_f32_e32 v130, v130
	v_exp_f32_e32 v131, v131
	v_exp_f32_e32 v132, v132
	v_exp_f32_e32 v133, v133
	v_exp_f32_e32 v134, v134
	v_exp_f32_e32 v135, v135
	v_mfma_f32_32x32x16_bf16 v[2:17], v[180:183], v[156:159], v[2:17]
	v_exp_f32_e32 v136, v136
	v_exp_f32_e32 v137, v137
	v_exp_f32_e32 v138, v138
	v_exp_f32_e32 v139, v139
	v_exp_f32_e32 v140, v140
	v_exp_f32_e32 v141, v141
	v_exp_f32_e32 v142, v142
	v_exp_f32_e32 v143, v143
	v_cvt_pk_bf16_f32 v184, v128, v129
	v_cvt_pk_bf16_f32 v185, v130, v131
	v_cvt_pk_bf16_f32 v186, v132, v133
	v_cvt_pk_bf16_f32 v187, v134, v135
	v_cvt_pk_bf16_f32 v188, v136, v137
	v_cvt_pk_bf16_f32 v189, v138, v139
	v_cvt_pk_bf16_f32 v190, v140, v141
	v_cvt_pk_bf16_f32 v191, v142, v143
	v_permlane32_swap_b32_e32 v184, v186
	v_permlane32_swap_b32_e32 v185, v187
	v_permlane32_swap_b32_e32 v188, v190
	v_permlane32_swap_b32_e32 v189, v191
	v_add_f32_e32 v34, v34, v128
	v_add_f32_e32 v35, v35, v129
	v_mfma_f32_32x32x16_bf16 v[18:33], v[184:187], v[160:163], v[18:33]
	v_add_f32_e32 v36, v36, v130
	v_add_f32_e32 v37, v37, v131
	v_add_f32_e32 v38, v38, v132
	v_add_f32_e32 v39, v39, v133
	v_add_f32_e32 v40, v40, v134
	v_add_f32_e32 v41, v41, v135
	v_add_f32_e32 v42, v42, v136
	v_add_f32_e32 v43, v43, v137
	v_mfma_f32_32x32x16_bf16 v[2:17], v[184:187], v[164:167], v[2:17]
	v_add_f32_e32 v44, v44, v138
	v_add_f32_e32 v45, v45, v139
	v_add_f32_e32 v46, v46, v140
	v_add_f32_e32 v47, v47, v141
	v_add_f32_e32 v48, v48, v142
	v_add_f32_e32 v49, v49, v143
	v_add_f32_e32 v35, v35, v34
	v_add_f32_e32 v36, v36, v35
	v_mfma_f32_32x32x16_bf16 v[18:33], v[188:191], v[168:171], v[18:33]
	v_add_f32_e32 v37, v37, v36
	v_add_f32_e32 v38, v38, v37
	v_add_f32_e32 v39, v39, v38
	v_add_f32_e32 v40, v40, v39
	v_add_f32_e32 v41, v41, v40
	v_add_f32_e32 v42, v42, v41
	v_add_f32_e32 v43, v43, v42
	v_add_f32_e32 v44, v44, v43
	v_mfma_f32_32x32x16_bf16 v[2:17], v[188:191], v[172:175], v[2:17]
	v_add_f32_e32 v45, v45, v44
	v_add_f32_e32 v46, v46, v45
	v_add_f32_e32 v47, v47, v46
	v_add_f32_e32 v48, v48, v47
	v_add_f32_e32 v49, v49, v48
	v_add_f32_e32 v127, v127, v49
	s_add_i32 s14, s14, 2
	s_and_b32 s14, s14, 3
	s_add_i32 s15, s15, 2
	s_waitcnt vmcnt(0) lgkmcnt(0)
	s_barrier
	s_cmp_lt_u32 s15, s96
	s_cbranch_scc1 .LBB0_536
